# same as previous but without the static priority raise for waves 4-7
# baseline (speedup 1.0000x reference)
; __device__ __forceinline__ float bflo(unsigned u) { return __uint_as_float(u << 16); }
; __device__ __forceinline__ float bfhi(unsigned u) { return __uint_as_float(u & 0xffff0000u); }
; #define DMA_WAIT_BAR() do { asm volatile("s_waitcnt vmcnt(0)" ::: "memory"); __syncthreads(); } while (0)
; #define RD_K(slot) do { const LAS unsigned char* kp_ = L + (slot) * ASLOT; \
;         _Pragma("unroll") for (int st = 0; st < 4; ++st) { kf[2 * st] = *(const LAS bf16x8*)(kp_ + (kb0 ^ (32 * st))); kf[2 * st + 1] = *(const LAS bf16x8*)(kp_ + 8192 + (kb0 ^ (32 * st))); } } while (0)
; __device__ __forceinline__ void attn_unit(LAS unsigned char* L, bf16_t* QKV, size_t rowbase, int S, int h, int qb, float lam, const float* subln, unsigned* kmax) {
;     ...
;         const int seq = rowbase < (size_t)TP ? (int)(rowbase >> 14) : 2 + (int)((rowbase - TP) >> 13);
;         unsigned* kp = kmax + (seq * 16 + 2 * h + hd) * 2;
;         const float kb = sqrtf(__uint_as_float(__hip_atomic_load(kp, __ATOMIC_RELAXED, __HIP_MEMORY_SCOPE_AGENT)) + __uint_as_float(__hip_atomic_load(kp + 1, __ATOMIC_RELAXED, __HIP_MEMORY_SCOPE_AGENT)));
;         float q2 = 0.f;
; #pragma unroll
;         for (int st = 0; st < 4; ++st) { const u32x4 w = __builtin_bit_cast(u32x4, qf[st]);
;             q2 += ((bflo(w.x) * bflo(w.x) + bfhi(w.x) * bfhi(w.x)) + (bflo(w.y) * bflo(w.y) + bfhi(w.y) * bfhi(w.y))) + ((bflo(w.z) * bflo(w.z) + bfhi(w.z) * bfhi(w.z)) + (bflo(w.w) * bflo(w.w) + bfhi(w.w) * bfhi(w.w))); }
;         q2 += __shfl_xor(q2, 32);
;         const float mref = sqrtf(q2) * kb;
; #pragma unroll
;         for (int r = 0; r < 16; ++r) negm[r] = -mref; }
;     DMA_WAIT_BAR();
;     bf16x8 kf[8], va[4], vb[4];
;     ...
;     RD_K(0);
.LBB0_926:
	s_lshl_b32 s5, s63, 2
	s_lshl_b32 s10, s40, 1
	s_lshl_b32 s4, s22, 5
	s_add_i32 s5, s10, s5
	s_add_i32 s10, s5, s4
	s_lshl_b32 s23, s40, 3
	s_lshl_b64 s[4:5], s[10:11], 2
	s_add_u32 s4, s26, s4
	s_addc_u32 s5, s27, s5
	global_load_dword v25, v157, s[4:5] sc1
	global_load_dword v27, v157, s[4:5] offset:4 sc1
	s_waitcnt vmcnt(5)
	v_and_b32_e32 v3, 0xffff0000, v113
	v_and_b32_e32 v2, 0xffff0000, v112
	v_and_b32_e32 v7, 0xffff0000, v115
	v_and_b32_e32 v6, 0xffff0000, v114
	s_waitcnt vmcnt(4)
	v_and_b32_e32 v11, 0xffff0000, v117
	v_and_b32_e32 v10, 0xffff0000, v116
	v_and_b32_e32 v15, 0xffff0000, v119
	v_and_b32_e32 v14, 0xffff0000, v118
	v_lshlrev_b32_e32 v1, 16, v113
	v_lshlrev_b32_e32 v0, 16, v112
	v_lshlrev_b32_e32 v5, 16, v115
	v_lshlrev_b32_e32 v4, 16, v114
	v_lshlrev_b32_e32 v9, 16, v117
	v_lshlrev_b32_e32 v8, 16, v116
	v_lshlrev_b32_e32 v13, 16, v119
	v_lshlrev_b32_e32 v12, 16, v118
	v_pk_mul_f32 v[2:3], v[2:3], v[2:3]
	v_pk_mul_f32 v[6:7], v[6:7], v[6:7]
	v_pk_mul_f32 v[10:11], v[10:11], v[10:11]
	v_pk_mul_f32 v[14:15], v[14:15], v[14:15]
	s_waitcnt vmcnt(2)
	v_lshlrev_b32_e32 v24, 16, v124
	v_and_b32_e32 v26, 0xffff0000, v124
	v_lshlrev_b32_e32 v28, 16, v125
	v_and_b32_e32 v29, 0xffff0000, v125
	v_pk_fma_f32 v[0:1], v[0:1], v[0:1], v[2:3]
	v_pk_fma_f32 v[2:3], v[4:5], v[4:5], v[6:7]
	v_pk_fma_f32 v[4:5], v[8:9], v[8:9], v[10:11]
	v_pk_fma_f32 v[6:7], v[12:13], v[12:13], v[14:15]
	v_mul_f32_e32 v35, v24, v24
	v_mul_f32_e32 v36, v26, v26
	v_mul_f32_e32 v37, v28, v28
	v_mul_f32_e32 v29, v29, v29
	v_pk_add_f32 v[0:1], v[0:1], v[0:1] op_sel:[0,1] op_sel_hi:[1,0]
	v_pk_add_f32 v[2:3], v[2:3], v[2:3] op_sel:[0,1] op_sel_hi:[1,0]
	v_pk_add_f32 v[4:5], v[4:5], v[4:5] op_sel:[0,1] op_sel_hi:[1,0]
	v_pk_add_f32 v[6:7], v[6:7], v[6:7] op_sel:[0,1] op_sel_hi:[1,0]
	v_mov_b32_e32 v1, v35
	v_mov_b32_e32 v3, v36
	v_mov_b32_e32 v5, v37
	v_mov_b32_e32 v7, v29
	v_pk_add_f32 v[0:1], v[0:1], v[2:3]
	v_pk_add_f32 v[2:3], v[4:5], v[6:7]
	v_and_b32_e32 v17, 0xffff0000, v120
	v_and_b32_e32 v19, 0xffff0000, v121
	v_and_b32_e32 v21, 0xffff0000, v122
	v_and_b32_e32 v23, 0xffff0000, v123
	v_lshlrev_b32_e32 v30, 16, v126
	v_and_b32_e32 v31, 0xffff0000, v126
	v_pk_add_f32 v[0:1], v[0:1], v[2:3]
	v_lshlrev_b32_e32 v16, 16, v120
	v_lshlrev_b32_e32 v18, 16, v121
	v_lshlrev_b32_e32 v20, 16, v122
	v_lshlrev_b32_e32 v22, 16, v123
	v_lshlrev_b32_e32 v32, 16, v127
	v_and_b32_e32 v33, 0xffff0000, v127
	v_mul_f32_e32 v38, v30, v30
	v_mul_f32_e32 v31, v31, v31
	v_mul_f32_e32 v24, v17, v17
	v_mul_f32_e32 v26, v19, v19
	v_mul_f32_e32 v28, v21, v21
	v_mul_f32_e32 v30, v23, v23
	v_mul_f32_e32 v32, v32, v32
	v_mul_f32_e32 v33, v33, v33
	v_pk_fma_f32 v[12:13], v[20:21], v[20:21], v[28:29] op_sel_hi:[1,1,0]
	v_pk_fma_f32 v[14:15], v[22:23], v[22:23], v[30:31] op_sel_hi:[1,1,0]
	v_mov_b32_e32 v13, v32
	v_mov_b32_e32 v15, v33
	v_and_b32_e32 v6, 64, v186
	v_add_u32_e32 v6, 64, v6
	v_bitop3_b32 v34, s23, v171, v181 bitop3:0x36
	v_lshl_add_u32 v34, v34, 4, v172
	v_add_u32_e32 v188, 0, v34
	s_waitcnt vmcnt(0)
	s_barrier
	ds_read_b128 v[80:83], v188
	ds_read_b128 v[128:131], v188 offset:8192
	v_mov_b32_e32 v187, 0
	s_waitcnt vmcnt(1)
	v_pk_fma_f32 v[8:9], v[16:17], v[16:17], v[24:25] op_sel_hi:[1,1,0]
	s_waitcnt vmcnt(0)
	v_add_f32_e32 v2, v27, v25
	v_mul_f32_e32 v3, 0x4f800000, v2
	v_cmp_gt_f32_e32 vcc, s37, v2
	v_pk_fma_f32 v[10:11], v[18:19], v[18:19], v[26:27] op_sel_hi:[1,1,0]
	v_mov_b32_e32 v9, v38
	v_cndmask_b32_e32 v4, v2, v3, vcc
	v_mov_b32_e32 v11, v31
	v_sqrt_f32_e32 v5, v4
	v_pk_add_f32 v[8:9], v[8:9], v[10:11]
	v_pk_add_f32 v[10:11], v[12:13], v[14:15]
	s_add_i32 s24, s42, -1
	v_pk_add_f32 v[2:3], v[8:9], v[10:11]
	s_add_i32 s25, s43, 0x1c000
	v_pk_add_f32 v[0:1], v[0:1], v[2:3]
	v_xor_b32_e32 v3, 32, v186
	v_add_f32_e32 v0, v0, v1
	v_add_u32_e32 v1, -1, v5
	v_fma_f32 v2, -v1, v5, v4
	v_cmp_ge_f32_e64 s[4:5], 0, v2
	v_add_u32_e32 v2, 1, v5
	s_add_i32 s63, s43, 0x1e000
	v_cndmask_b32_e64 v1, v5, v1, s[4:5]
	v_cmp_lt_i32_e64 s[4:5], v3, v6
	v_fma_f32 v5, -v2, v5, v4
	s_mov_b32 s68, 7
	v_cndmask_b32_e64 v3, v186, v3, s[4:5]
	v_lshlrev_b32_e32 v156, 2, v3
	ds_bpermute_b32 v3, v156, v0
	v_cmp_lt_f32_e64 s[4:5], 0, v5
	v_mov_b32_e32 v192, 0
	v_mov_b32_e32 v193, 0
	v_cndmask_b32_e64 v1, v1, v2, s[4:5]
	s_waitcnt lgkmcnt(0)
; #define DMA_WAIT_BAR() do { asm volatile("s_waitcnt vmcnt(0)" ::: "memory"); __syncthreads(); } while (0)
; #define RD_K(slot) do { const LAS unsigned char* kp_ = L + (slot) * ASLOT; \
;         _Pragma("unroll") for (int st = 0; st < 4; ++st) { kf[2 * st] = *(const LAS bf16x8*)(kp_ + (kb0 ^ (32 * st))); kf[2 * st + 1] = *(const LAS bf16x8*)(kp_ + 8192 + (kb0 ^ (32 * st))); } } while (0)
; __device__ __forceinline__ void attn_unit(LAS unsigned char* L, bf16_t* QKV, size_t rowbase, int S, int h, int qb, float lam, const float* subln, unsigned* kmax) {
;     ...
;         const float mref = sqrtf(q2) * kb;
; #pragma unroll
;         for (int r = 0; r < 16; ++r) negm[r] = -mref; }
;     DMA_WAIT_BAR();
;     bf16x8 kf[8], va[4], vb[4];
;     ...
;     RD_K(0);
;     __syncthreads();
;     bf16x8 pf[4];
	v_add_f32_e32 v0, v0, v3
	v_mul_f32_e32 v3, 0x4f800000, v0
	v_cmp_gt_f32_e64 s[4:5], s37, v0
	v_mul_f32_e32 v2, 0x37800000, v1
	v_cndmask_b32_e32 v1, v1, v2, vcc
	v_cndmask_b32_e64 v0, v0, v3, s[4:5]
	v_sqrt_f32_e32 v3, v0
	v_cmp_class_f32_e32 vcc, v4, v173
	v_mov_b32_e32 v194, 0
	v_mov_b32_e32 v5, v187
	v_add_u32_e32 v2, -1, v3
	v_cndmask_b32_e32 v1, v1, v4, vcc
	v_fma_f32 v4, -v2, v3, v0
	v_cmp_ge_f32_e32 vcc, 0, v4
	v_add_u32_e32 v4, 1, v3
	v_mov_b32_e32 v6, v187
	v_cndmask_b32_e32 v2, v3, v2, vcc
	v_fma_f32 v3, -v4, v3, v0
	v_cmp_lt_f32_e32 vcc, 0, v3
	v_mov_b32_e32 v7, v187
	v_mov_b32_e32 v8, v187
	v_cndmask_b32_e32 v2, v2, v4, vcc
	v_mul_f32_e32 v3, 0x37800000, v2
	v_cndmask_b32_e64 v2, v2, v3, s[4:5]
	v_cmp_class_f32_e32 vcc, v0, v173
	v_mov_b32_e32 v3, v187
	v_mov_b32_e32 v4, v187
	v_cndmask_b32_e32 v0, v2, v0, vcc
	v_mul_f32_e64 v64, v0, -v1
	v_xor_b32_e32 v0, 32, v34
	v_add_u32_e32 v189, 0, v0
	v_xor_b32_e32 v0, 64, v34
	v_add_u32_e32 v190, 0, v0
	v_xor_b32_e32 v0, 0x60, v34
	v_add_u32_e32 v191, 0, v0
	ds_read_b128 v[132:135], v189
	ds_read_b128 v[136:139], v189 offset:8192
	ds_read_b128 v[140:143], v190
	ds_read_b128 v[144:147], v190 offset:8192
	ds_read_b128 v[148:151], v191
	ds_read_b128 v[152:155], v191 offset:8192
	v_mov_b32_e32 v65, v64
	v_mov_b32_e32 v66, v64
	v_mov_b32_e32 v67, v64
	v_mov_b32_e32 v68, v64
	v_mov_b32_e32 v69, v64
	v_mov_b32_e32 v70, v64
	v_mov_b32_e32 v71, v64
	v_mov_b32_e32 v72, v64
	v_mov_b32_e32 v73, v64
	v_mov_b32_e32 v74, v64
	v_mov_b32_e32 v75, v64
	v_mov_b32_e32 v76, v64
	v_mov_b32_e32 v77, v64
	v_mov_b32_e32 v78, v64
	v_mov_b32_e32 v79, v64
	v_mov_b32_e32 v0, 0
	v_mov_b32_e32 v1, v187
	v_mov_b32_e32 v2, v187
	v_mov_b32_e32 v9, v187
	v_mov_b32_e32 v10, v187
	v_mov_b32_e32 v11, v187
	v_mov_b32_e32 v12, v187
	v_mov_b32_e32 v13, v187
	v_mov_b32_e32 v14, v187
	v_mov_b32_e32 v15, v187
	v_mov_b32_e32 v16, 0
	v_mov_b32_e32 v17, v187
	v_mov_b32_e32 v18, v187
	v_mov_b32_e32 v19, v187
	v_mov_b32_e32 v20, v187
	v_mov_b32_e32 v21, v187
	v_mov_b32_e32 v22, v187
	v_mov_b32_e32 v23, v187
	v_mov_b32_e32 v24, v187
	v_mov_b32_e32 v25, v187
	v_mov_b32_e32 v26, v187
	v_mov_b32_e32 v27, v187
	v_mov_b32_e32 v28, v187
	v_mov_b32_e32 v29, v187
	v_mov_b32_e32 v30, v187
	v_mov_b32_e32 v31, v187
	v_mov_b32_e32 v32, 0
	v_mov_b32_e32 v33, v187
	v_mov_b32_e32 v34, v187
	v_mov_b32_e32 v35, v187
	v_mov_b32_e32 v36, v187
	v_mov_b32_e32 v37, v187
	v_mov_b32_e32 v38, v187
	v_mov_b32_e32 v39, v187
	v_mov_b32_e32 v40, v187
	v_mov_b32_e32 v41, v187
	v_mov_b32_e32 v42, v187
	v_mov_b32_e32 v43, v187
	v_mov_b32_e32 v44, v187
	v_mov_b32_e32 v45, v187
	v_mov_b32_e32 v46, v187
	v_mov_b32_e32 v47, v187
	v_mov_b32_e32 v48, 0
	v_mov_b32_e32 v49, v187
	v_mov_b32_e32 v50, v187
	v_mov_b32_e32 v51, v187
	v_mov_b32_e32 v52, v187
	v_mov_b32_e32 v53, v187
	v_mov_b32_e32 v54, v187
	v_mov_b32_e32 v55, v187
	v_mov_b32_e32 v56, v187
	v_mov_b32_e32 v57, v187
	v_mov_b32_e32 v58, v187
	v_mov_b32_e32 v59, v187
	v_mov_b32_e32 v60, v187
	v_mov_b32_e32 v61, v187
	v_mov_b32_e32 v62, v187
	v_mov_b32_e32 v63, v187
	s_add_u32 s22, s20, 0x10000
	s_addc_u32 s23, s21, 0
	v_add_u32_e32 v254, 0x4000, v163
	v_add_u32_e32 v255, 0x100, v163
	v_add_u32_e32 v253, 0x4100, v163
	s_waitcnt lgkmcnt(0)
	s_barrier
.LBB0_927:
	s_add_i32 s69, s68, -3
	s_add_i32 s10, s68, -4
	s_min_u32 s10, s10, s24
	s_lshl_b32 s10, s10, 15
	s_add_u32 s4, s20, s10
	s_addc_u32 s5, s21, 0
	ds_read_b64_tr_b16 v[224:225], v174
	ds_read_b64_tr_b16 v[226:227], v175 offset:2048
	ds_read_b64_tr_b16 v[228:229], v176
	ds_read_b64_tr_b16 v[230:231], v177 offset:2048
	ds_read_b64_tr_b16 v[232:233], v178
	ds_read_b64_tr_b16 v[234:235], v179 offset:2048
	ds_read_b64_tr_b16 v[236:237], v183
	ds_read_b64_tr_b16 v[238:239], v184 offset:2048
	s_mov_b32 m0, s53
	v_mfma_f32_32x32x16_bf16 v[96:111], v[132:135], v[116:119], v[64:79]
	global_load_lds_dwordx4 v163, s[4:5]
	s_mov_b32 m0, s58
	v_mfma_f32_32x32x16_bf16 v[96:111], v[140:143], v[120:123], v[96:111]
	global_load_lds_dwordx4 v254, s[4:5]
	s_mov_b32 m0, s59
	v_mfma_f32_32x32x16_bf16 v[96:111], v[148:151], v[124:127], v[96:111]
	global_load_lds_dwordx4 v255, s[22:23]
	ds_read_b64_tr_b16 v[132:133], v176 offset:4096
	ds_read_b64_tr_b16 v[134:135], v177 offset:6144
	s_mov_b32 m0, s61
	v_mfma_f32_32x32x16_bf16 v[96:111], v[80:83], v[112:115], v[96:111]
	global_load_lds_dwordx4 v253, s[22:23]
	ds_read_b64_tr_b16 v[140:141], v183 offset:4096
	ds_read_b64_tr_b16 v[142:143], v184 offset:6144
	v_mfma_f32_32x32x16_bf16 v[80:95], v[128:131], v[112:115], v[64:79]
	ds_read_b64_tr_b16 v[128:129], v174 offset:4096
	ds_read_b64_tr_b16 v[130:131], v175 offset:6144
	v_mfma_f32_32x32x16_bf16 v[80:95], v[136:139], v[116:119], v[80:95]
	s_nop 3
	v_mfma_f32_32x32x16_bf16 v[80:95], v[144:147], v[120:123], v[80:95]
	v_exp_f32_e32 v96, v96
	v_exp_f32_e32 v97, v97
	v_exp_f32_e32 v98, v98
	v_mfma_f32_32x32x16_bf16 v[80:95], v[152:155], v[124:127], v[80:95]
	v_exp_f32_e32 v99, v99
	v_exp_f32_e32 v100, v100
	v_exp_f32_e32 v101, v101
	v_exp_f32_e32 v102, v102
	v_exp_f32_e32 v103, v103
	v_cvt_pk_bf16_f32 v208, v96, v97
	v_cvt_pk_bf16_f32 v209, v98, v99
	v_cvt_pk_bf16_f32 v210, v100, v101
	v_cvt_pk_bf16_f32 v211, v102, v103
	v_exp_f32_e32 v104, v104
	v_exp_f32_e32 v105, v105
	s_waitcnt lgkmcnt(6)
	v_mfma_f32_32x32x16_bf16 v[48:63], v[224:227], v[208:211], v[48:63]
	v_exp_f32_e32 v106, v106
	v_exp_f32_e32 v107, v107
	v_exp_f32_e32 v108, v108
	ds_read_b64_tr_b16 v[136:137], v178 offset:4096
	ds_read_b64_tr_b16 v[138:139], v179 offset:6144
	v_mfma_f32_32x32x16_bf16 v[32:47], v[228:231], v[208:211], v[32:47]
	v_exp_f32_e32 v109, v109
	v_exp_f32_e32 v110, v110
	v_exp_f32_e32 v111, v111
	ds_read_b64_tr_b16 v[144:145], v174 offset:8192
	ds_read_b64_tr_b16 v[146:147], v175 offset:10240
	v_mfma_f32_32x32x16_bf16 v[16:31], v[232:235], v[208:211], v[16:31]
	v_cvt_pk_bf16_f32 v212, v104, v105
	v_cvt_pk_bf16_f32 v213, v106, v107
	v_cvt_pk_bf16_f32 v214, v108, v109
	v_cvt_pk_bf16_f32 v215, v110, v111
	v_add_f32_e32 v187, v96, v187
	v_add_f32_e32 v192, v97, v192
	ds_read_b64_tr_b16 v[148:149], v176 offset:8192
	ds_read_b64_tr_b16 v[150:151], v177 offset:10240
	v_mfma_f32_32x32x16_bf16 v[0:15], v[236:239], v[208:211], v[0:15]
	v_add_f32_e32 v193, v98, v193
	v_add_f32_e32 v194, v99, v194
	v_add_f32_e32 v187, v100, v187
	v_add_f32_e32 v192, v101, v192
	v_add_f32_e32 v193, v102, v193
	v_add_f32_e32 v194, v103, v194
	ds_read_b64_tr_b16 v[152:153], v178 offset:8192
	ds_read_b64_tr_b16 v[154:155], v179 offset:10240
	s_waitcnt lgkmcnt(6)
	v_mfma_f32_32x32x16_bf16 v[48:63], v[128:131], v[212:215], v[48:63]
	v_exp_f32_e32 v80, v80
	v_exp_f32_e32 v81, v81
	v_exp_f32_e32 v82, v82
	ds_read_b64_tr_b16 v[240:241], v183 offset:8192
	ds_read_b64_tr_b16 v[242:243], v184 offset:10240
	ds_read_b128 v[128:131], v188 offset:24576
	v_mfma_f32_32x32x16_bf16 v[32:47], v[132:135], v[212:215], v[32:47]
	v_exp_f32_e32 v83, v83
	v_exp_f32_e32 v84, v84
	v_exp_f32_e32 v85, v85
	ds_read_b64_tr_b16 v[196:197], v174 offset:12288
	ds_read_b64_tr_b16 v[198:199], v175 offset:14336
	ds_read_b128 v[132:135], v189 offset:16384
	v_mfma_f32_32x32x16_bf16 v[16:31], v[136:139], v[212:215], v[16:31]
	v_exp_f32_e32 v86, v86
	v_exp_f32_e32 v87, v87
	v_cvt_pk_bf16_f32 v216, v80, v81
	v_cvt_pk_bf16_f32 v217, v82, v83
	ds_read_b64_tr_b16 v[200:201], v176 offset:12288
	ds_read_b64_tr_b16 v[202:203], v177 offset:14336
	ds_read_b128 v[136:139], v189 offset:24576
	v_mfma_f32_32x32x16_bf16 v[0:15], v[140:143], v[212:215], v[0:15]
	v_cvt_pk_bf16_f32 v218, v84, v85
	v_cvt_pk_bf16_f32 v219, v86, v87
	v_add_f32_e32 v187, v104, v187
	v_add_f32_e32 v192, v105, v192
	v_add_f32_e32 v193, v106, v193
	v_add_f32_e32 v194, v107, v194
	s_waitcnt lgkmcnt(10)
	ds_read_b64_tr_b16 v[204:205], v178 offset:12288
	ds_read_b64_tr_b16 v[206:207], v179 offset:14336
	ds_read_b128 v[140:143], v190 offset:16384
	s_waitcnt lgkmcnt(10)
	v_mfma_f32_32x32x16_bf16 v[48:63], v[144:147], v[216:219], v[48:63]
	v_exp_f32_e32 v88, v88
	v_exp_f32_e32 v89, v89
	v_exp_f32_e32 v90, v90
	ds_read_b64_tr_b16 v[246:247], v183 offset:12288
	ds_read_b64_tr_b16 v[248:249], v184 offset:14336
	ds_read_b128 v[144:147], v190 offset:24576
	v_mfma_f32_32x32x16_bf16 v[32:47], v[148:151], v[216:219], v[32:47]
	v_exp_f32_e32 v91, v91
	v_exp_f32_e32 v92, v92
	v_exp_f32_e32 v93, v93
	ds_read_b128 v[148:151], v191 offset:16384
	v_mfma_f32_32x32x16_bf16 v[16:31], v[152:155], v[216:219], v[16:31]
	v_exp_f32_e32 v94, v94
	v_exp_f32_e32 v95, v95
	v_cvt_pk_bf16_f32 v220, v88, v89
	v_cvt_pk_bf16_f32 v221, v90, v91
	ds_read_b128 v[152:155], v191 offset:24576
	v_mfma_f32_32x32x16_bf16 v[0:15], v[240:243], v[216:219], v[0:15]
	v_cvt_pk_bf16_f32 v222, v92, v93
	v_cvt_pk_bf16_f32 v223, v94, v95
	v_add_f32_e32 v187, v80, v187
	v_add_f32_e32 v192, v81, v192
	v_add_f32_e32 v193, v82, v193
	v_add_f32_e32 v194, v83, v194
	s_waitcnt lgkmcnt(3)
	v_mfma_f32_32x32x16_bf16 v[48:63], v[196:199], v[220:223], v[48:63]
	v_add_f32_e32 v187, v108, v187
	v_add_f32_e32 v192, v109, v192
	v_add_f32_e32 v193, v110, v193
	v_add_f32_e32 v194, v111, v194
	v_add_f32_e32 v187, v84, v187
	v_add_f32_e32 v192, v85, v192
	ds_read_b128 v[80:83], v188 offset:16384
	v_mfma_f32_32x32x16_bf16 v[32:47], v[200:203], v[220:223], v[32:47]
	v_add_f32_e32 v193, v86, v193
	v_add_f32_e32 v194, v87, v194
	v_add_f32_e32 v187, v88, v187
	v_add_f32_e32 v192, v89, v192
	v_add_f32_e32 v193, v90, v193
	v_add_f32_e32 v194, v91, v194
	v_mfma_f32_32x32x16_bf16 v[16:31], v[204:207], v[220:223], v[16:31]
	v_add_f32_e32 v187, v92, v187
	v_add_f32_e32 v192, v93, v192
	v_add_f32_e32 v193, v94, v193
	v_add_f32_e32 v194, v95, v194
	v_mfma_f32_32x32x16_bf16 v[0:15], v[246:249], v[220:223], v[0:15]
	s_waitcnt vmcnt(4)
	s_waitcnt lgkmcnt(0)
	s_barrier
; __device__ __forceinline__ void attn_unit(LAS unsigned char* L, bf16_t* QKV, size_t rowbase, int S, int h, int qb, float lam, const float* subln, unsigned* kmax) {
;     ...
;     for (int t = 0; t < NT; t += 4) { TILE(t, 0); TILE(t + 1, 1); TILE(t + 2, 2); TILE(t + 3, 3); }
	s_add_i32 s10, s68, -3
	s_min_u32 s10, s10, s24
	s_lshl_b32 s10, s10, 15
	s_add_u32 s22, s20, s10
	s_addc_u32 s23, s21, 0
	ds_read_b64_tr_b16 v[224:225], v174 offset:16384
	ds_read_b64_tr_b16 v[226:227], v175 offset:18432
	ds_read_b64_tr_b16 v[228:229], v176 offset:16384
	ds_read_b64_tr_b16 v[230:231], v177 offset:18432
	ds_read_b64_tr_b16 v[232:233], v178 offset:16384
	ds_read_b64_tr_b16 v[234:235], v179 offset:18432
	ds_read_b64_tr_b16 v[236:237], v183 offset:16384
	ds_read_b64_tr_b16 v[238:239], v184 offset:18432
	s_mov_b32 m0, s43
	v_mfma_f32_32x32x16_bf16 v[96:111], v[132:135], v[116:119], v[64:79]
	global_load_lds_dwordx4 v163, s[22:23]
	s_mov_b32 m0, s45
	v_mfma_f32_32x32x16_bf16 v[96:111], v[140:143], v[120:123], v[96:111]
	global_load_lds_dwordx4 v254, s[22:23]
	s_mov_b32 m0, s25
	v_mfma_f32_32x32x16_bf16 v[96:111], v[148:151], v[124:127], v[96:111]
	global_load_lds_dwordx4 v255, s[4:5]
	ds_read_b64_tr_b16 v[132:133], v176 offset:20480
	ds_read_b64_tr_b16 v[134:135], v177 offset:22528
	s_mov_b32 m0, s63
	v_mfma_f32_32x32x16_bf16 v[96:111], v[80:83], v[112:115], v[96:111]
	global_load_lds_dwordx4 v253, s[4:5]
	ds_read_b64_tr_b16 v[140:141], v183 offset:20480
	ds_read_b64_tr_b16 v[142:143], v184 offset:22528
	v_mfma_f32_32x32x16_bf16 v[80:95], v[128:131], v[112:115], v[64:79]
	ds_read_b64_tr_b16 v[128:129], v174 offset:20480
	ds_read_b64_tr_b16 v[130:131], v175 offset:22528
	v_mfma_f32_32x32x16_bf16 v[80:95], v[136:139], v[116:119], v[80:95]
	s_nop 3
	v_mfma_f32_32x32x16_bf16 v[80:95], v[144:147], v[120:123], v[80:95]
	v_exp_f32_e32 v96, v96
	v_exp_f32_e32 v97, v97
	v_exp_f32_e32 v98, v98
	v_mfma_f32_32x32x16_bf16 v[80:95], v[152:155], v[124:127], v[80:95]
	v_exp_f32_e32 v99, v99
	v_exp_f32_e32 v100, v100
	v_exp_f32_e32 v101, v101
	v_exp_f32_e32 v102, v102
	v_exp_f32_e32 v103, v103
	v_cvt_pk_bf16_f32 v208, v96, v97
	v_cvt_pk_bf16_f32 v209, v98, v99
	v_cvt_pk_bf16_f32 v210, v100, v101
	v_cvt_pk_bf16_f32 v211, v102, v103
	v_exp_f32_e32 v104, v104
	v_exp_f32_e32 v105, v105
	s_waitcnt lgkmcnt(6)
	v_mfma_f32_32x32x16_bf16 v[48:63], v[224:227], v[208:211], v[48:63]
	v_exp_f32_e32 v106, v106
	v_exp_f32_e32 v107, v107
	v_exp_f32_e32 v108, v108
	ds_read_b64_tr_b16 v[136:137], v178 offset:20480
	ds_read_b64_tr_b16 v[138:139], v179 offset:22528
	v_mfma_f32_32x32x16_bf16 v[32:47], v[228:231], v[208:211], v[32:47]
	v_exp_f32_e32 v109, v109
	v_exp_f32_e32 v110, v110
	v_exp_f32_e32 v111, v111
	ds_read_b64_tr_b16 v[144:145], v174 offset:24576
	ds_read_b64_tr_b16 v[146:147], v175 offset:26624
	v_mfma_f32_32x32x16_bf16 v[16:31], v[232:235], v[208:211], v[16:31]
	v_cvt_pk_bf16_f32 v212, v104, v105
	v_cvt_pk_bf16_f32 v213, v106, v107
	v_cvt_pk_bf16_f32 v214, v108, v109
	v_cvt_pk_bf16_f32 v215, v110, v111
	v_add_f32_e32 v187, v96, v187
	v_add_f32_e32 v192, v97, v192
	ds_read_b64_tr_b16 v[148:149], v176 offset:24576
	ds_read_b64_tr_b16 v[150:151], v177 offset:26624
	v_mfma_f32_32x32x16_bf16 v[0:15], v[236:239], v[208:211], v[0:15]
	v_add_f32_e32 v193, v98, v193
	v_add_f32_e32 v194, v99, v194
	v_add_f32_e32 v187, v100, v187
	v_add_f32_e32 v192, v101, v192
	v_add_f32_e32 v193, v102, v193
	v_add_f32_e32 v194, v103, v194
	ds_read_b64_tr_b16 v[152:153], v178 offset:24576
	ds_read_b64_tr_b16 v[154:155], v179 offset:26624
	s_waitcnt lgkmcnt(6)
	v_mfma_f32_32x32x16_bf16 v[48:63], v[128:131], v[212:215], v[48:63]
	v_exp_f32_e32 v80, v80
	v_exp_f32_e32 v81, v81
	v_exp_f32_e32 v82, v82
	ds_read_b64_tr_b16 v[240:241], v183 offset:24576
	ds_read_b64_tr_b16 v[242:243], v184 offset:26624
	ds_read_b128 v[128:131], v188 offset:40960
	v_mfma_f32_32x32x16_bf16 v[32:47], v[132:135], v[212:215], v[32:47]
	v_exp_f32_e32 v83, v83
	v_exp_f32_e32 v84, v84
	v_exp_f32_e32 v85, v85
	ds_read_b64_tr_b16 v[196:197], v174 offset:28672
	ds_read_b64_tr_b16 v[198:199], v175 offset:30720
	ds_read_b128 v[132:135], v189 offset:32768
	v_mfma_f32_32x32x16_bf16 v[16:31], v[136:139], v[212:215], v[16:31]
	v_exp_f32_e32 v86, v86
	v_exp_f32_e32 v87, v87
	v_cvt_pk_bf16_f32 v216, v80, v81
	v_cvt_pk_bf16_f32 v217, v82, v83
	ds_read_b64_tr_b16 v[200:201], v176 offset:28672
	ds_read_b64_tr_b16 v[202:203], v177 offset:30720
	ds_read_b128 v[136:139], v189 offset:40960
	v_mfma_f32_32x32x16_bf16 v[0:15], v[140:143], v[212:215], v[0:15]
	v_cvt_pk_bf16_f32 v218, v84, v85
	v_cvt_pk_bf16_f32 v219, v86, v87
	v_add_f32_e32 v187, v104, v187
	v_add_f32_e32 v192, v105, v192
	v_add_f32_e32 v193, v106, v193
	v_add_f32_e32 v194, v107, v194
	s_waitcnt lgkmcnt(10)
	ds_read_b64_tr_b16 v[204:205], v178 offset:28672
	ds_read_b64_tr_b16 v[206:207], v179 offset:30720
	ds_read_b128 v[140:143], v190 offset:32768
	s_waitcnt lgkmcnt(10)
	v_mfma_f32_32x32x16_bf16 v[48:63], v[144:147], v[216:219], v[48:63]
	v_exp_f32_e32 v88, v88
	v_exp_f32_e32 v89, v89
	v_exp_f32_e32 v90, v90
	ds_read_b64_tr_b16 v[246:247], v183 offset:28672
	ds_read_b64_tr_b16 v[248:249], v184 offset:30720
	ds_read_b128 v[144:147], v190 offset:40960
	v_mfma_f32_32x32x16_bf16 v[32:47], v[148:151], v[216:219], v[32:47]
	v_exp_f32_e32 v91, v91
	v_exp_f32_e32 v92, v92
	v_exp_f32_e32 v93, v93
	ds_read_b128 v[148:151], v191 offset:32768
	v_mfma_f32_32x32x16_bf16 v[16:31], v[152:155], v[216:219], v[16:31]
	v_exp_f32_e32 v94, v94
	v_exp_f32_e32 v95, v95
	v_cvt_pk_bf16_f32 v220, v88, v89
	v_cvt_pk_bf16_f32 v221, v90, v91
	ds_read_b128 v[152:155], v191 offset:40960
	v_mfma_f32_32x32x16_bf16 v[0:15], v[240:243], v[216:219], v[0:15]
	v_cvt_pk_bf16_f32 v222, v92, v93
	v_cvt_pk_bf16_f32 v223, v94, v95
	v_add_f32_e32 v187, v80, v187
	v_add_f32_e32 v192, v81, v192
	v_add_f32_e32 v193, v82, v193
	v_add_f32_e32 v194, v83, v194
	s_waitcnt lgkmcnt(3)
	v_mfma_f32_32x32x16_bf16 v[48:63], v[196:199], v[220:223], v[48:63]
	v_add_f32_e32 v187, v108, v187
	v_add_f32_e32 v192, v109, v192
	v_add_f32_e32 v193, v110, v193
	v_add_f32_e32 v194, v111, v194
	v_add_f32_e32 v187, v84, v187
	v_add_f32_e32 v192, v85, v192
	ds_read_b128 v[80:83], v188 offset:32768
	v_mfma_f32_32x32x16_bf16 v[32:47], v[200:203], v[220:223], v[32:47]
	v_add_f32_e32 v193, v86, v193
	v_add_f32_e32 v194, v87, v194
	v_add_f32_e32 v187, v88, v187
	v_add_f32_e32 v192, v89, v192
	v_add_f32_e32 v193, v90, v193
	v_add_f32_e32 v194, v91, v194
	v_mfma_f32_32x32x16_bf16 v[16:31], v[204:207], v[220:223], v[16:31]
	v_add_f32_e32 v187, v92, v187
	v_add_f32_e32 v192, v93, v192
	v_add_f32_e32 v193, v94, v193
	v_add_f32_e32 v194, v95, v194
	v_mfma_f32_32x32x16_bf16 v[0:15], v[246:249], v[220:223], v[0:15]
	s_waitcnt vmcnt(4)
	s_waitcnt lgkmcnt(0)
	s_barrier
; __device__ __forceinline__ void attn_unit(LAS unsigned char* L, bf16_t* QKV, size_t rowbase, int S, int h, int qb, float lam, const float* subln, unsigned* kmax) {
;     ...
;     for (int t = 0; t < NT; t += 4) { TILE(t, 0); TILE(t + 1, 1); TILE(t + 2, 2); TILE(t + 3, 3); }
	s_add_i32 s10, s68, -2
	s_min_u32 s10, s10, s24
	s_lshl_b32 s10, s10, 15
	s_add_u32 s4, s20, s10
	s_addc_u32 s5, s21, 0
	ds_read_b64_tr_b16 v[224:225], v174 offset:32768
	ds_read_b64_tr_b16 v[226:227], v175 offset:34816
	ds_read_b64_tr_b16 v[228:229], v176 offset:32768
	ds_read_b64_tr_b16 v[230:231], v177 offset:34816
	ds_read_b64_tr_b16 v[232:233], v178 offset:32768
	ds_read_b64_tr_b16 v[234:235], v179 offset:34816
	ds_read_b64_tr_b16 v[236:237], v183 offset:32768
	ds_read_b64_tr_b16 v[238:239], v184 offset:34816
	s_mov_b32 m0, s46
	v_mfma_f32_32x32x16_bf16 v[96:111], v[132:135], v[116:119], v[64:79]
	global_load_lds_dwordx4 v163, s[4:5]
	s_mov_b32 m0, s47
	v_mfma_f32_32x32x16_bf16 v[96:111], v[140:143], v[120:123], v[96:111]
	global_load_lds_dwordx4 v254, s[4:5]
	s_mov_b32 m0, s44
	v_mfma_f32_32x32x16_bf16 v[96:111], v[148:151], v[124:127], v[96:111]
	global_load_lds_dwordx4 v255, s[22:23]
	ds_read_b64_tr_b16 v[132:133], v176 offset:36864
	ds_read_b64_tr_b16 v[134:135], v177 offset:38912
	s_mov_b32 m0, s48
	v_mfma_f32_32x32x16_bf16 v[96:111], v[80:83], v[112:115], v[96:111]
	global_load_lds_dwordx4 v253, s[22:23]
	ds_read_b64_tr_b16 v[140:141], v183 offset:36864
	ds_read_b64_tr_b16 v[142:143], v184 offset:38912
	v_mfma_f32_32x32x16_bf16 v[80:95], v[128:131], v[112:115], v[64:79]
	ds_read_b64_tr_b16 v[128:129], v174 offset:36864
	ds_read_b64_tr_b16 v[130:131], v175 offset:38912
	v_mfma_f32_32x32x16_bf16 v[80:95], v[136:139], v[116:119], v[80:95]
	s_nop 3
	v_mfma_f32_32x32x16_bf16 v[80:95], v[144:147], v[120:123], v[80:95]
	v_exp_f32_e32 v96, v96
	v_exp_f32_e32 v97, v97
	v_exp_f32_e32 v98, v98
	v_mfma_f32_32x32x16_bf16 v[80:95], v[152:155], v[124:127], v[80:95]
	v_exp_f32_e32 v99, v99
	v_exp_f32_e32 v100, v100
	v_exp_f32_e32 v101, v101
	v_exp_f32_e32 v102, v102
	v_exp_f32_e32 v103, v103
	v_cvt_pk_bf16_f32 v208, v96, v97
	v_cvt_pk_bf16_f32 v209, v98, v99
	v_cvt_pk_bf16_f32 v210, v100, v101
	v_cvt_pk_bf16_f32 v211, v102, v103
	v_exp_f32_e32 v104, v104
	v_exp_f32_e32 v105, v105
	s_waitcnt lgkmcnt(6)
	v_mfma_f32_32x32x16_bf16 v[48:63], v[224:227], v[208:211], v[48:63]
	v_exp_f32_e32 v106, v106
	v_exp_f32_e32 v107, v107
	v_exp_f32_e32 v108, v108
	ds_read_b64_tr_b16 v[136:137], v178 offset:36864
	ds_read_b64_tr_b16 v[138:139], v179 offset:38912
	v_mfma_f32_32x32x16_bf16 v[32:47], v[228:231], v[208:211], v[32:47]
	v_exp_f32_e32 v109, v109
	v_exp_f32_e32 v110, v110
	v_exp_f32_e32 v111, v111
	ds_read_b64_tr_b16 v[144:145], v174 offset:40960
	ds_read_b64_tr_b16 v[146:147], v175 offset:43008
	v_mfma_f32_32x32x16_bf16 v[16:31], v[232:235], v[208:211], v[16:31]
	v_cvt_pk_bf16_f32 v212, v104, v105
	v_cvt_pk_bf16_f32 v213, v106, v107
	v_cvt_pk_bf16_f32 v214, v108, v109
	v_cvt_pk_bf16_f32 v215, v110, v111
	v_add_f32_e32 v187, v96, v187
	v_add_f32_e32 v192, v97, v192
	ds_read_b64_tr_b16 v[148:149], v176 offset:40960
	ds_read_b64_tr_b16 v[150:151], v177 offset:43008
	v_mfma_f32_32x32x16_bf16 v[0:15], v[236:239], v[208:211], v[0:15]
	v_add_f32_e32 v193, v98, v193
	v_add_f32_e32 v194, v99, v194
	v_add_f32_e32 v187, v100, v187
	v_add_f32_e32 v192, v101, v192
	v_add_f32_e32 v193, v102, v193
	v_add_f32_e32 v194, v103, v194
	ds_read_b64_tr_b16 v[152:153], v178 offset:40960
	ds_read_b64_tr_b16 v[154:155], v179 offset:43008
	s_waitcnt lgkmcnt(6)
	v_mfma_f32_32x32x16_bf16 v[48:63], v[128:131], v[212:215], v[48:63]
	v_exp_f32_e32 v80, v80
	v_exp_f32_e32 v81, v81
	v_exp_f32_e32 v82, v82
	ds_read_b64_tr_b16 v[240:241], v183 offset:40960
	ds_read_b64_tr_b16 v[242:243], v184 offset:43008
	ds_read_b128 v[128:131], v188 offset:57344
	v_mfma_f32_32x32x16_bf16 v[32:47], v[132:135], v[212:215], v[32:47]
	v_exp_f32_e32 v83, v83
	v_exp_f32_e32 v84, v84
	v_exp_f32_e32 v85, v85
	ds_read_b64_tr_b16 v[196:197], v174 offset:45056
	ds_read_b64_tr_b16 v[198:199], v175 offset:47104
	ds_read_b128 v[132:135], v189 offset:49152
	v_mfma_f32_32x32x16_bf16 v[16:31], v[136:139], v[212:215], v[16:31]
	v_exp_f32_e32 v86, v86
	v_exp_f32_e32 v87, v87
	v_cvt_pk_bf16_f32 v216, v80, v81
	v_cvt_pk_bf16_f32 v217, v82, v83
	ds_read_b64_tr_b16 v[200:201], v176 offset:45056
	ds_read_b64_tr_b16 v[202:203], v177 offset:47104
	ds_read_b128 v[136:139], v189 offset:57344
	v_mfma_f32_32x32x16_bf16 v[0:15], v[140:143], v[212:215], v[0:15]
	v_cvt_pk_bf16_f32 v218, v84, v85
	v_cvt_pk_bf16_f32 v219, v86, v87
	v_add_f32_e32 v187, v104, v187
	v_add_f32_e32 v192, v105, v192
	v_add_f32_e32 v193, v106, v193
	v_add_f32_e32 v194, v107, v194
	s_waitcnt lgkmcnt(10)
	ds_read_b64_tr_b16 v[204:205], v178 offset:45056
	ds_read_b64_tr_b16 v[206:207], v179 offset:47104
	ds_read_b128 v[140:143], v190 offset:49152
	s_waitcnt lgkmcnt(10)
	v_mfma_f32_32x32x16_bf16 v[48:63], v[144:147], v[216:219], v[48:63]
	v_exp_f32_e32 v88, v88
	v_exp_f32_e32 v89, v89
	v_exp_f32_e32 v90, v90
	ds_read_b64_tr_b16 v[246:247], v183 offset:45056
	ds_read_b64_tr_b16 v[248:249], v184 offset:47104
	ds_read_b128 v[144:147], v190 offset:57344
	v_mfma_f32_32x32x16_bf16 v[32:47], v[148:151], v[216:219], v[32:47]
	v_exp_f32_e32 v91, v91
	v_exp_f32_e32 v92, v92
	v_exp_f32_e32 v93, v93
	ds_read_b128 v[148:151], v191 offset:49152
	v_mfma_f32_32x32x16_bf16 v[16:31], v[152:155], v[216:219], v[16:31]
	v_exp_f32_e32 v94, v94
	v_exp_f32_e32 v95, v95
	v_cvt_pk_bf16_f32 v220, v88, v89
	v_cvt_pk_bf16_f32 v221, v90, v91
	ds_read_b128 v[152:155], v191 offset:57344
	v_mfma_f32_32x32x16_bf16 v[0:15], v[240:243], v[216:219], v[0:15]
	v_cvt_pk_bf16_f32 v222, v92, v93
	v_cvt_pk_bf16_f32 v223, v94, v95
	v_add_f32_e32 v187, v80, v187
	v_add_f32_e32 v192, v81, v192
	v_add_f32_e32 v193, v82, v193
	v_add_f32_e32 v194, v83, v194
	s_waitcnt lgkmcnt(3)
	v_mfma_f32_32x32x16_bf16 v[48:63], v[196:199], v[220:223], v[48:63]
	v_add_f32_e32 v187, v108, v187
	v_add_f32_e32 v192, v109, v192
	v_add_f32_e32 v193, v110, v193
	v_add_f32_e32 v194, v111, v194
	v_add_f32_e32 v187, v84, v187
	v_add_f32_e32 v192, v85, v192
	ds_read_b128 v[80:83], v188 offset:49152
	v_mfma_f32_32x32x16_bf16 v[32:47], v[200:203], v[220:223], v[32:47]
	v_add_f32_e32 v193, v86, v193
	v_add_f32_e32 v194, v87, v194
	v_add_f32_e32 v187, v88, v187
	v_add_f32_e32 v192, v89, v192
	v_add_f32_e32 v193, v90, v193
	v_add_f32_e32 v194, v91, v194
	v_mfma_f32_32x32x16_bf16 v[16:31], v[204:207], v[220:223], v[16:31]
	v_add_f32_e32 v187, v92, v187
	v_add_f32_e32 v192, v93, v192
	v_add_f32_e32 v193, v94, v193
	v_add_f32_e32 v194, v95, v194
	v_mfma_f32_32x32x16_bf16 v[0:15], v[246:249], v[220:223], v[0:15]
	s_waitcnt vmcnt(4)
	s_waitcnt lgkmcnt(0)
	s_barrier
; __device__ __forceinline__ void attn_unit(LAS unsigned char* L, bf16_t* QKV, size_t rowbase, int S, int h, int qb, float lam, const float* subln, unsigned* kmax) {
;     ...
;     for (int t = 0; t < NT; t += 4) { TILE(t, 0); TILE(t + 1, 1); TILE(t + 2, 2); TILE(t + 3, 3); }
	s_add_i32 s10, s68, -1
	s_min_u32 s10, s10, s24
	s_lshl_b32 s10, s10, 15
	s_add_u32 s22, s20, s10
	s_addc_u32 s23, s21, 0
	ds_read_b64_tr_b16 v[224:225], v174 offset:49152
	ds_read_b64_tr_b16 v[226:227], v175 offset:51200
	ds_read_b64_tr_b16 v[228:229], v176 offset:49152
	ds_read_b64_tr_b16 v[230:231], v177 offset:51200
	ds_read_b64_tr_b16 v[232:233], v178 offset:49152
	ds_read_b64_tr_b16 v[234:235], v179 offset:51200
	ds_read_b64_tr_b16 v[236:237], v183 offset:49152
	ds_read_b64_tr_b16 v[238:239], v184 offset:51200
	s_mov_b32 m0, s49
	v_mfma_f32_32x32x16_bf16 v[96:111], v[132:135], v[116:119], v[64:79]
	global_load_lds_dwordx4 v163, s[22:23]
	s_mov_b32 m0, s50
	v_mfma_f32_32x32x16_bf16 v[96:111], v[140:143], v[120:123], v[96:111]
	global_load_lds_dwordx4 v254, s[22:23]
	s_mov_b32 m0, s51
	v_mfma_f32_32x32x16_bf16 v[96:111], v[148:151], v[124:127], v[96:111]
	global_load_lds_dwordx4 v255, s[4:5]
	ds_read_b64_tr_b16 v[132:133], v176 offset:53248
	ds_read_b64_tr_b16 v[134:135], v177 offset:55296
	s_mov_b32 m0, s52
	v_mfma_f32_32x32x16_bf16 v[96:111], v[80:83], v[112:115], v[96:111]
	global_load_lds_dwordx4 v253, s[4:5]
	ds_read_b64_tr_b16 v[140:141], v183 offset:53248
	ds_read_b64_tr_b16 v[142:143], v184 offset:55296
	v_mfma_f32_32x32x16_bf16 v[80:95], v[128:131], v[112:115], v[64:79]
	ds_read_b64_tr_b16 v[128:129], v174 offset:53248
	ds_read_b64_tr_b16 v[130:131], v175 offset:55296
	v_mfma_f32_32x32x16_bf16 v[80:95], v[136:139], v[116:119], v[80:95]
	s_nop 3
	v_mfma_f32_32x32x16_bf16 v[80:95], v[144:147], v[120:123], v[80:95]
	v_exp_f32_e32 v96, v96
	v_exp_f32_e32 v97, v97
	v_exp_f32_e32 v98, v98
	v_mfma_f32_32x32x16_bf16 v[80:95], v[152:155], v[124:127], v[80:95]
	v_exp_f32_e32 v99, v99
	v_exp_f32_e32 v100, v100
	v_exp_f32_e32 v101, v101
	v_exp_f32_e32 v102, v102
	v_exp_f32_e32 v103, v103
	v_cvt_pk_bf16_f32 v208, v96, v97
	v_cvt_pk_bf16_f32 v209, v98, v99
	v_cvt_pk_bf16_f32 v210, v100, v101
	v_cvt_pk_bf16_f32 v211, v102, v103
	v_exp_f32_e32 v104, v104
	v_exp_f32_e32 v105, v105
	s_waitcnt lgkmcnt(6)
	v_mfma_f32_32x32x16_bf16 v[48:63], v[224:227], v[208:211], v[48:63]
	v_exp_f32_e32 v106, v106
	v_exp_f32_e32 v107, v107
	v_exp_f32_e32 v108, v108
	ds_read_b64_tr_b16 v[136:137], v178 offset:53248
	ds_read_b64_tr_b16 v[138:139], v179 offset:55296
	v_mfma_f32_32x32x16_bf16 v[32:47], v[228:231], v[208:211], v[32:47]
	v_exp_f32_e32 v109, v109
	v_exp_f32_e32 v110, v110
	v_exp_f32_e32 v111, v111
	ds_read_b64_tr_b16 v[144:145], v174 offset:57344
	ds_read_b64_tr_b16 v[146:147], v175 offset:59392
	v_mfma_f32_32x32x16_bf16 v[16:31], v[232:235], v[208:211], v[16:31]
	v_cvt_pk_bf16_f32 v212, v104, v105
	v_cvt_pk_bf16_f32 v213, v106, v107
	v_cvt_pk_bf16_f32 v214, v108, v109
	v_cvt_pk_bf16_f32 v215, v110, v111
	v_add_f32_e32 v187, v96, v187
	v_add_f32_e32 v192, v97, v192
	ds_read_b64_tr_b16 v[148:149], v176 offset:57344
	ds_read_b64_tr_b16 v[150:151], v177 offset:59392
	v_mfma_f32_32x32x16_bf16 v[0:15], v[236:239], v[208:211], v[0:15]
	v_add_f32_e32 v193, v98, v193
	v_add_f32_e32 v194, v99, v194
	v_add_f32_e32 v187, v100, v187
	v_add_f32_e32 v192, v101, v192
	v_add_f32_e32 v193, v102, v193
	v_add_f32_e32 v194, v103, v194
	ds_read_b64_tr_b16 v[152:153], v178 offset:57344
	ds_read_b64_tr_b16 v[154:155], v179 offset:59392
	s_waitcnt lgkmcnt(6)
	v_mfma_f32_32x32x16_bf16 v[48:63], v[128:131], v[212:215], v[48:63]
	v_exp_f32_e32 v80, v80
	v_exp_f32_e32 v81, v81
	v_exp_f32_e32 v82, v82
	ds_read_b64_tr_b16 v[240:241], v183 offset:57344
	ds_read_b64_tr_b16 v[242:243], v184 offset:59392
	ds_read_b128 v[128:131], v188 offset:8192
	v_mfma_f32_32x32x16_bf16 v[32:47], v[132:135], v[212:215], v[32:47]
	v_exp_f32_e32 v83, v83
	v_exp_f32_e32 v84, v84
	v_exp_f32_e32 v85, v85
	ds_read_b64_tr_b16 v[196:197], v174 offset:61440
	ds_read_b64_tr_b16 v[198:199], v175 offset:63488
	ds_read_b128 v[132:135], v189
	v_mfma_f32_32x32x16_bf16 v[16:31], v[136:139], v[212:215], v[16:31]
	v_exp_f32_e32 v86, v86
	v_exp_f32_e32 v87, v87
	v_cvt_pk_bf16_f32 v216, v80, v81
	v_cvt_pk_bf16_f32 v217, v82, v83
	ds_read_b64_tr_b16 v[200:201], v176 offset:61440
	ds_read_b64_tr_b16 v[202:203], v177 offset:63488
	ds_read_b128 v[136:139], v189 offset:8192
	v_mfma_f32_32x32x16_bf16 v[0:15], v[140:143], v[212:215], v[0:15]
	v_cvt_pk_bf16_f32 v218, v84, v85
	v_cvt_pk_bf16_f32 v219, v86, v87
	v_add_f32_e32 v187, v104, v187
	v_add_f32_e32 v192, v105, v192
	v_add_f32_e32 v193, v106, v193
	v_add_f32_e32 v194, v107, v194
	s_waitcnt lgkmcnt(10)
	ds_read_b64_tr_b16 v[204:205], v178 offset:61440
	ds_read_b64_tr_b16 v[206:207], v179 offset:63488
	ds_read_b128 v[140:143], v190
	s_waitcnt lgkmcnt(10)
	v_mfma_f32_32x32x16_bf16 v[48:63], v[144:147], v[216:219], v[48:63]
	v_exp_f32_e32 v88, v88
	v_exp_f32_e32 v89, v89
	v_exp_f32_e32 v90, v90
	ds_read_b64_tr_b16 v[246:247], v183 offset:61440
	ds_read_b64_tr_b16 v[248:249], v184 offset:63488
	ds_read_b128 v[144:147], v190 offset:8192
	v_mfma_f32_32x32x16_bf16 v[32:47], v[148:151], v[216:219], v[32:47]
	v_exp_f32_e32 v91, v91
	v_exp_f32_e32 v92, v92
	v_exp_f32_e32 v93, v93
	ds_read_b128 v[148:151], v191
	v_mfma_f32_32x32x16_bf16 v[16:31], v[152:155], v[216:219], v[16:31]
	v_exp_f32_e32 v94, v94
	v_exp_f32_e32 v95, v95
	v_cvt_pk_bf16_f32 v220, v88, v89
	v_cvt_pk_bf16_f32 v221, v90, v91
	ds_read_b128 v[152:155], v191 offset:8192
	v_mfma_f32_32x32x16_bf16 v[0:15], v[240:243], v[216:219], v[0:15]
	v_cvt_pk_bf16_f32 v222, v92, v93
	v_cvt_pk_bf16_f32 v223, v94, v95
	v_add_f32_e32 v187, v80, v187
	v_add_f32_e32 v192, v81, v192
	v_add_f32_e32 v193, v82, v193
	v_add_f32_e32 v194, v83, v194
	s_waitcnt lgkmcnt(3)
	v_mfma_f32_32x32x16_bf16 v[48:63], v[196:199], v[220:223], v[48:63]
	v_add_f32_e32 v187, v108, v187
	v_add_f32_e32 v192, v109, v192
	v_add_f32_e32 v193, v110, v193
	v_add_f32_e32 v194, v111, v194
	v_add_f32_e32 v187, v84, v187
	v_add_f32_e32 v192, v85, v192
	ds_read_b128 v[80:83], v188
	v_mfma_f32_32x32x16_bf16 v[32:47], v[200:203], v[220:223], v[32:47]
	v_add_f32_e32 v193, v86, v193
	v_add_f32_e32 v194, v87, v194
	v_add_f32_e32 v187, v88, v187
	v_add_f32_e32 v192, v89, v192
	v_add_f32_e32 v193, v90, v193
	v_add_f32_e32 v194, v91, v194
	v_mfma_f32_32x32x16_bf16 v[16:31], v[204:207], v[220:223], v[16:31]
	v_add_f32_e32 v187, v92, v187
	v_add_f32_e32 v192, v93, v192
	v_add_f32_e32 v193, v94, v193
	v_add_f32_e32 v194, v95, v194
	v_mfma_f32_32x32x16_bf16 v[0:15], v[246:249], v[220:223], v[0:15]
	s_waitcnt vmcnt(4)
	s_add_i32 s68, s68, 4
	s_cmp_ge_u32 s69, s42
	s_waitcnt lgkmcnt(0)
	s_barrier
; #define LAS __attribute__((address_space(3)))
; #define DMA_WAIT_BAR() do { asm volatile("s_waitcnt vmcnt(0)" ::: "memory"); __syncthreads(); } while (0)
; __device__ __forceinline__ void attn_unit(LAS unsigned char* L, bf16_t* QKV, size_t rowbase, int S, int h, int qb, float lam, const float* subln, unsigned* kmax) {
;     ...
;     DMA_WAIT_BAR();
;     ...
;     lsum = (lsum + lsb) + (lsc + lsd);
;     const float inv = 1.f / (lsum + __shfl_xor(lsum, 32));
;     LAS float* X = (LAS float*)L;
;     const int xo = (32 * qblk + r32) * AXP + 4 * hi;
;     if (hd == 1) { const float sc = inv * lam;
; #pragma unroll
;         for (int d = 0; d < 4; ++d)
; #pragma unroll
;             for (int rg = 0; rg < 4; ++rg) *(LAS f32x4*)(X + xo + 32 * d + 8 * rg) = (f32x4){o[d][4 * rg] * sc, o[d][4 * rg + 1] * sc, o[d][4 * rg + 2] * sc, o[d][4 * rg + 3] * sc}; }
	s_cbranch_scc0 .LBB0_927
	v_add_f32_e32 v64, v187, v192
	v_add_f32_e32 v65, v193, v194
	v_add_f32_e32 v64, v64, v65
	ds_bpermute_b32 v65, v156, v64
	s_waitcnt vmcnt(0)
	s_cmp_eq_u32 s40, 1
	s_waitcnt lgkmcnt(0)
	s_barrier
	v_add_f32_e32 v64, v64, v65
	v_div_scale_f32 v65, s[4:5], v64, v64, 1.0
	v_rcp_f32_e32 v66, v65
	s_nop 0
	v_fma_f32 v67, -v65, v66, 1.0
	v_fmac_f32_e32 v66, v67, v66
	v_div_scale_f32 v67, vcc, 1.0, v64, 1.0
	v_mul_f32_e32 v68, v67, v66
	v_fma_f32 v69, -v65, v68, v67
	v_fmac_f32_e32 v68, v69, v66
	v_fma_f32 v65, -v65, v68, v67
	v_div_fmas_f32 v65, v65, v66, v68
	v_div_fixup_f32 v66, v65, v64, 1.0
	v_or_b32_e32 v64, s41, v182
	v_mad_u32_u24 v64, v64, s38, v158
	v_lshl_add_u32 v64, v64, 2, 0
	s_cbranch_scc0 .LBB0_930
	v_mul_f32_e32 v72, v159, v66
	v_pk_mul_f32 v[68:69], v[48:49], v[72:73] op_sel_hi:[1,0]
	v_pk_mul_f32 v[70:71], v[50:51], v[72:73] op_sel_hi:[1,0]
	ds_write_b128 v64, v[68:71]
	v_pk_mul_f32 v[68:69], v[52:53], v[72:73] op_sel_hi:[1,0]
	v_pk_mul_f32 v[70:71], v[54:55], v[72:73] op_sel_hi:[1,0]
	ds_write_b128 v64, v[68:71] offset:32
	v_pk_mul_f32 v[68:69], v[56:57], v[72:73] op_sel_hi:[1,0]
	v_pk_mul_f32 v[70:71], v[58:59], v[72:73] op_sel_hi:[1,0]
	ds_write_b128 v64, v[68:71] offset:64
	v_pk_mul_f32 v[68:69], v[60:61], v[72:73] op_sel_hi:[1,0]
	v_pk_mul_f32 v[70:71], v[62:63], v[72:73] op_sel_hi:[1,0]
	ds_write_b128 v64, v[68:71] offset:96
	v_pk_mul_f32 v[68:69], v[32:33], v[72:73] op_sel_hi:[1,0]
	v_pk_mul_f32 v[70:71], v[34:35], v[72:73] op_sel_hi:[1,0]
	ds_write_b128 v64, v[68:71] offset:128
	v_pk_mul_f32 v[68:69], v[36:37], v[72:73] op_sel_hi:[1,0]
	v_pk_mul_f32 v[70:71], v[38:39], v[72:73] op_sel_hi:[1,0]
	ds_write_b128 v64, v[68:71] offset:160
	v_pk_mul_f32 v[68:69], v[40:41], v[72:73] op_sel_hi:[1,0]
	v_pk_mul_f32 v[70:71], v[42:43], v[72:73] op_sel_hi:[1,0]
	ds_write_b128 v64, v[68:71] offset:192
	v_pk_mul_f32 v[68:69], v[44:45], v[72:73] op_sel_hi:[1,0]
	v_pk_mul_f32 v[70:71], v[46:47], v[72:73] op_sel_hi:[1,0]
	ds_write_b128 v64, v[68:71] offset:224
	v_pk_mul_f32 v[68:69], v[16:17], v[72:73] op_sel_hi:[1,0]
	v_pk_mul_f32 v[70:71], v[18:19], v[72:73] op_sel_hi:[1,0]
	ds_write_b128 v64, v[68:71] offset:256
	v_pk_mul_f32 v[68:69], v[20:21], v[72:73] op_sel_hi:[1,0]
	v_pk_mul_f32 v[70:71], v[22:23], v[72:73] op_sel_hi:[1,0]
	ds_write_b128 v64, v[68:71] offset:288
	v_pk_mul_f32 v[68:69], v[24:25], v[72:73] op_sel_hi:[1,0]
	v_pk_mul_f32 v[70:71], v[26:27], v[72:73] op_sel_hi:[1,0]
	ds_write_b128 v64, v[68:71] offset:320
	v_pk_mul_f32 v[68:69], v[28:29], v[72:73] op_sel_hi:[1,0]
	v_pk_mul_f32 v[70:71], v[30:31], v[72:73] op_sel_hi:[1,0]
	ds_write_b128 v64, v[68:71] offset:352
	v_pk_mul_f32 v[68:69], v[0:1], v[72:73] op_sel_hi:[1,0]
	v_pk_mul_f32 v[70:71], v[2:3], v[72:73] op_sel_hi:[1,0]
	ds_write_b128 v64, v[68:71] offset:384
	v_pk_mul_f32 v[68:69], v[4:5], v[72:73] op_sel_hi:[1,0]
	v_pk_mul_f32 v[70:71], v[6:7], v[72:73] op_sel_hi:[1,0]
	ds_write_b128 v64, v[68:71] offset:416
	v_pk_mul_f32 v[68:69], v[8:9], v[72:73] op_sel_hi:[1,0]
	v_pk_mul_f32 v[70:71], v[10:11], v[72:73] op_sel_hi:[1,0]
	ds_write_b128 v64, v[68:71] offset:448
	v_pk_mul_f32 v[68:69], v[12:13], v[72:73] op_sel_hi:[1,0]
	v_pk_mul_f32 v[70:71], v[14:15], v[72:73] op_sel_hi:[1,0]
	ds_write_b128 v64, v[68:71] offset:480
